# P1: shift-image (cvec) wave tasks spread across all workgroups (t = wave*128 + widx) instead of eight per workgroup on 80 workgroups
# speedup vs baseline: 1.0075x; 1.0075x over previous
.LBB0_111:
	s_load_dwordx2 s[4:5], s[0:1], 0xd8
	s_mov_b32 s59, 1
	s_waitcnt lgkmcnt(0)
	s_cmp_lt_i32 s4, 2
	s_cselect_b64 s[4:5], -1, 0
	s_and_b64 s[2:3], s[4:5], s[2:3]
	s_andn2_b64 vcc, exec, s[2:3]
	s_cbranch_vccnz .LBB0_155
	s_cmp_lt_i32 s59, 1
	s_cbranch_scc1 .LBB0_155
	s_add_u32 s14, s86, 0x100000
	v_readlane_b32 s36, v250, 3
	s_addc_u32 s15, s87, 0
	s_lshl_b32 s4, s36, 3
	s_add_i32 s60, s4, s76
	s_lshl_b32 s61, s33, 3
	s_cmpk_lt_i32 s60, 0x4200
	s_cselect_b64 s[16:17], -1, 0
	s_add_u32 s18, s86, 0x900000
	s_addc_u32 s19, s87, 0
	s_add_u32 s20, s86, 0x4c00000
	s_addc_u32 s21, s87, 0
	s_cmpk_eq_i32 s33, 0x100
	s_cselect_b64 s[22:23], -1, 0
	s_and_b32 s4, s36, 0x7f
	s_lshl_b32 s5, s76, 7
	s_add_i32 s29, s4, s5
	s_bfe_i32 s4, s29, 0x10003
	s_lshl_b32 s5, s29, 3
	s_lshl_b32 s24, s29, 4
	s_and_b32 s4, s4, 0xb00
	s_and_b32 s5, s5, 0x3fffff80
	s_add_i32 s4, s4, s5
	s_and_b32 s5, s24, 0x70
	s_or_b32 s28, s4, s5
	s_add_i32 s4, s24, 0xfffff600
	s_lshl_b32 s6, s29, 7
	s_and_b32 s6, s6, 0x400
	s_lshr_b32 s4, s4, 1
	s_and_b32 s4, s4, 0x7fffff80
	s_or_b32 s5, s6, s5
	s_add_i32 s4, s4, s5
	s_lshl_b32 s5, s29, 5
	s_and_b32 s5, s5, 0xc0
	s_lshl_b32 s6, s29, 2
	s_and_b32 s7, s24, 0xf10
	s_and_b32 s6, s6, 32
	s_or_b32 s5, s7, s5
	s_addk_i32 s4, 0xa00
	s_or_b32 s5, s5, s6
	s_cmpk_lt_u32 s29, 0xa0
	s_load_dwordx4 s[8:11], s[0:1], 0x0
	s_load_dwordx2 s[12:13], s[0:1], 0x38
	s_cselect_b32 s30, s5, s4
	s_load_dwordx2 s[4:5], s[0:1], 0xa8
	s_load_dwordx2 s[6:7], s[0:1], 0x58
	s_cmpk_lt_u32 s36, 0x80
	s_movk_i32 s25, 0x1200
	s_cselect_b32 s31, 0, 0x3000
	s_cselect_b32 s62, s25, 0x1600
	s_waitcnt lgkmcnt(0)
	s_cselect_b32 s26, s6, s4
	s_mov_b32 s4, 0x500000
	s_cselect_b32 s27, s7, s5
	s_cselect_b32 s6, s4, 0x700000
	s_cselect_b32 s28, s30, s28
	s_add_u32 s30, s14, s31
	s_addc_u32 s31, s15, 0
	s_lshr_b32 s4, s62, 4
	s_mov_b32 s25, 0
	s_cmp_lt_u32 s29, s4
	s_cselect_b64 s[34:35], -1, 0
	s_lshl_b32 s63, s36, 9
	s_lshl_b32 s36, s33, 9
	s_lshl_b64 s[4:5], s[24:25], 2
	s_add_u32 s4, s86, s4
	s_addc_u32 s5, s87, s5
	s_add_u32 s38, s4, s6
	s_addc_u32 s39, s5, 0
	s_lshl_b32 s24, s62, 10
	s_lshl_b32 s40, s62, 2
	s_add_u32 s44, s86, 0xa80000
	s_addc_u32 s45, s87, 0
	s_ashr_i32 s37, s36, 31
	s_mov_b32 s29, s25
	s_mov_b32 s41, s25
	s_mul_i32 s42, s62, 0x64
	s_mov_b32 s43, s25
	s_lshl_b64 s[46:47], s[36:37], 2
	s_movk_i32 s37, 0x6000
	s_mov_b64 s[48:49], 0x1000
	s_movk_i32 s64, 0x1000
	v_mov_b32_e32 v83, 0
	s_movk_i32 s65, 0x810
	s_mov_b32 s66, 0x22000
	s_mov_b32 s67, 0x78787879
	s_mov_b32 s68, 0x21fff
	v_mov_b32_e32 v1, 0x4000
	v_mov_b32_e32 v90, 0x1000
	s_mov_b32 s69, s25
	s_branch .LBB0_115
